# token-prep loop: rope table load issued with the row loads (one memory round trip per token instead of two)
# baseline (speedup 1.0000x reference)
.LBB0_252:
	v_lshl_add_u64 v[56:57], s[28:29], 0, v[10:11]
	v_lshl_add_u64 v[58:59], s[28:29], 0, v[2:3]
	global_load_dwordx4 v[20:23], v[4:5], off offset:16
	global_load_dwordx4 v[24:27], v[4:5], off
	global_load_dwordx4 v[28:31], v[4:5], off offset:2064
	global_load_dwordx4 v[32:35], v[4:5], off offset:2048
	global_load_dwordx4 v[36:39], v[6:7], off offset:16
	global_load_dwordx4 v[40:43], v[6:7], off
	global_load_dwordx4 v[44:47], v[56:57], off offset:-1024
	global_load_dwordx4 v[48:51], v[56:57], off offset:-2048
	global_load_dwordx4 v[52:55], v[56:57], off offset:-3072
	global_load_ushort v1, v[58:59], off
	s_and_b32 s10, s2, 0x1ffe0
	v_or_b32_e32 v58, s10, v19
	v_lshl_add_u64 v[60:61], s[24:25], 0, v[10:11]
	v_lshlrev_b32_e32 v86, 3, v58
	s_nop 0
	global_load_dwordx2 v[92:93], v86, s[14:15]
	v_add_co_u32_e64 v56, s[8:9], s34, v60
	v_lshl_add_u64 v[62:63], s[20:21], 0, v[10:11]
	s_nop 0
	v_addc_co_u32_e64 v57, s[8:9], 0, v61, s[8:9]
	s_add_i32 s12, s12, s16
	s_add_i32 s2, s2, s3
	s_add_u32 s20, s20, s22
	s_addc_u32 s21, s21, s23
	s_add_u32 s24, s24, s26
	s_addc_u32 s25, s25, s27
	s_add_u32 s28, s28, s13
	s_addc_u32 s29, s29, s17
	s_cmpk_lt_i32 s12, 0x4000
	s_waitcnt vmcnt(0)
	v_lshlrev_b32_e32 v87, 16, v44
	v_and_b32_e32 v88, 0xffff0000, v44
	v_lshlrev_b32_e32 v44, 16, v52
	v_and_b32_e32 v58, 0xffff0000, v52
	v_lshlrev_b32_e32 v89, 16, v45
	v_and_b32_e32 v90, 0xffff0000, v45
	v_lshlrev_b32_e32 v45, 16, v48
	v_and_b32_e32 v59, 0xffff0000, v48
	v_lshlrev_b32_e32 v60, 16, v53
	v_and_b32_e32 v67, 0xffff0000, v46
	v_lshlrev_b32_e32 v66, 16, v46
	v_mul_f32_e32 v46, v44, v44
	v_mul_f32_e32 v70, v58, v58
	v_lshlrev_b32_e32 v61, 16, v49
	v_and_b32_e32 v48, 0xffff0000, v53
	v_and_b32_e32 v53, 0xffff0000, v54
	v_lshlrev_b32_e32 v52, 16, v54
	v_and_b32_e32 v65, 0xffff0000, v50
	v_lshlrev_b32_e32 v64, 16, v50
	v_and_b32_e32 v69, 0xffff0000, v55
	v_lshlrev_b32_e32 v68, 16, v55
	v_and_b32_e32 v55, 0xffff0000, v51
	v_lshlrev_b32_e32 v54, 16, v51
	v_and_b32_e32 v51, 0xffff0000, v47
	v_lshlrev_b32_e32 v50, 16, v47
	v_mul_f32_e32 v72, v60, v60
	v_pk_fma_f32 v[46:47], v[44:45], v[44:45], v[46:47] op_sel_hi:[1,1,0]
	v_pk_fma_f32 v[70:71], v[58:59], v[58:59], v[70:71] op_sel_hi:[1,1,0]
	v_and_b32_e32 v49, 0xffff0000, v49
	v_mul_f32_e32 v74, v48, v48
	v_pk_fma_f32 v[72:73], v[60:61], v[60:61], v[72:73] op_sel_hi:[1,1,0]
	v_mul_f32_e32 v46, v87, v87
	v_mul_f32_e32 v70, v88, v88
	v_pk_mul_f32 v[76:77], v[64:65], v[64:65]
	v_pk_fma_f32 v[74:75], v[48:49], v[48:49], v[74:75] op_sel_hi:[1,1,0]
	v_mul_f32_e32 v72, v89, v89
	v_pk_add_f32 v[46:47], v[46:47], v[70:71]
	v_pk_mul_f32 v[78:79], v[66:67], v[66:67]
	v_pk_fma_f32 v[76:77], v[52:53], v[52:53], v[76:77]
	v_mul_f32_e32 v74, v90, v90
	v_pk_add_f32 v[46:47], v[72:73], v[46:47]
	v_pk_mul_f32 v[80:81], v[54:55], v[54:55]
	v_mov_b32_e32 v84, v78
	v_mov_b32_e32 v85, v76
	v_pk_add_f32 v[46:47], v[74:75], v[46:47]
	v_pk_mul_f32 v[82:83], v[50:51], v[50:51]
	v_pk_fma_f32 v[80:81], v[68:69], v[68:69], v[80:81]
	v_mov_b32_e32 v76, v79
	v_pk_add_f32 v[46:47], v[84:85], v[46:47]
	v_mov_b32_e32 v78, v82
	v_mov_b32_e32 v79, v80
	v_pk_add_f32 v[46:47], v[76:77], v[46:47]
	v_mov_b32_e32 v80, v83
	v_pk_add_f32 v[46:47], v[78:79], v[46:47]
	v_lshlrev_b32_e32 v1, 16, v1
	v_pk_add_f32 v[46:47], v[80:81], v[46:47]
	ds_bpermute_b32 v71, v13, v47
	ds_bpermute_b32 v70, v13, v46
	s_waitcnt lgkmcnt(0)
	v_pk_add_f32 v[46:47], v[46:47], v[70:71]
	ds_bpermute_b32 v71, v14, v47
	ds_bpermute_b32 v70, v14, v46
	s_waitcnt lgkmcnt(0)
	v_pk_add_f32 v[46:47], v[46:47], v[70:71]
	ds_bpermute_b32 v71, v15, v47
	ds_bpermute_b32 v70, v15, v46
	s_waitcnt lgkmcnt(0)
	v_pk_add_f32 v[46:47], v[46:47], v[70:71]
	ds_bpermute_b32 v71, v16, v47
	ds_bpermute_b32 v70, v16, v46
	s_waitcnt lgkmcnt(0)
	v_pk_add_f32 v[46:47], v[46:47], v[70:71]
	ds_bpermute_b32 v71, v17, v47
	ds_bpermute_b32 v70, v17, v46
	s_waitcnt lgkmcnt(0)
	v_pk_add_f32 v[46:47], v[46:47], v[70:71]
	ds_bpermute_b32 v71, v18, v47
	ds_bpermute_b32 v70, v18, v46
	s_waitcnt lgkmcnt(0)
	v_pk_add_f32 v[46:47], v[46:47], v[70:71]
	s_nop 0
	v_pk_fma_f32 v[46:47], v[46:47], s[30:31], v[12:13] op_sel_hi:[1,1,0]
	s_nop 0
	v_mul_f32_e32 v70, 0x4b800000, v47
	v_cmp_gt_f32_e64 s[10:11], s33, v47
	v_mul_f32_e32 v71, 0x4b800000, v46
	v_cmp_gt_f32_e64 s[8:9], s33, v46
	v_cndmask_b32_e64 v47, v47, v70, s[10:11]
	v_rsq_f32_e32 v47, v47
	v_cndmask_b32_e64 v46, v46, v71, s[8:9]
	v_rsq_f32_e32 v46, v46
	v_mul_f32_e32 v70, 0x45800000, v47
	v_cndmask_b32_e64 v47, v47, v70, s[10:11]
	v_mul_f32_e32 v71, 0x45800000, v46
	v_mul_f32_e32 v23, v47, v23
	v_cndmask_b32_e64 v46, v46, v71, s[8:9]
	v_mul_f32_e32 v24, v24, v47
	v_mul_f32_e32 v32, v32, v47
	v_mul_f32_e32 v25, v25, v47
	v_mul_f32_e32 v26, v26, v47
	v_mul_f32_e32 v27, v27, v47
	v_mul_f32_e32 v20, v47, v20
	v_mul_f32_e32 v21, v47, v21
	v_mul_f32_e32 v22, v47, v22
	v_mul_f32_e32 v23, v23, v69
	v_mul_f32_e32 v40, v40, v46
	v_mul_f32_e32 v33, v33, v47
	v_mul_f32_e32 v41, v41, v46
	v_mul_f32_e32 v34, v34, v47
	v_mul_f32_e32 v42, v42, v46
	v_mul_f32_e32 v35, v35, v47
	v_mul_f32_e32 v43, v46, v43
	v_mul_f32_e32 v28, v47, v28
	v_mul_f32_e32 v36, v46, v36
	v_mul_f32_e32 v29, v47, v29
	v_mul_f32_e32 v37, v46, v37
	v_mul_f32_e32 v30, v47, v30
	v_mul_f32_e32 v38, v46, v38
	v_mul_f32_e32 v31, v47, v31
	v_mul_f32_e32 v39, v46, v39
	v_mul_f32_e32 v24, v24, v44
	v_mul_f32_e32 v32, v32, v45
	v_mul_f32_e32 v25, v25, v58
	v_mul_f32_e32 v26, v26, v60
	v_mul_f32_e32 v27, v27, v48
	v_mul_f32_e32 v44, v20, v52
	v_mul_f32_e32 v45, v21, v53
	v_mul_f32_e32 v46, v22, v68
	v_cvt_pk_bf16_f32 v20, v24, v25
	v_cvt_pk_bf16_f32 v21, v26, v27
	v_cvt_pk_bf16_f32 v22, v44, v45
	v_cvt_pk_bf16_f32 v23, v46, v23
	v_mul_f32_e32 v33, v33, v59
	v_mul_f32_e32 v34, v34, v61
	v_mul_f32_e32 v35, v35, v49
	v_mul_f32_e32 v28, v28, v64
	v_mul_f32_e32 v29, v29, v65
	v_mul_f32_e32 v30, v30, v54
	v_mul_f32_e32 v31, v31, v55
	global_store_dwordx4 v[56:57], v[20:23], off
	v_mul_f32_e32 v40, v40, v87
	v_mul_f32_e32 v41, v41, v88
	v_cvt_pk_bf16_f32 v20, v32, v33
	v_cvt_pk_bf16_f32 v21, v34, v35
	v_cvt_pk_bf16_f32 v22, v28, v29
	v_cvt_pk_bf16_f32 v23, v30, v31
	v_mul_f32_e32 v42, v42, v89
	v_mul_f32_e32 v43, v43, v90
	v_mul_f32_e32 v36, v36, v66
	v_mul_f32_e32 v37, v37, v67
	v_mul_f32_e32 v38, v38, v50
	v_mul_f32_e32 v39, v39, v51
	global_store_dwordx4 v[56:57], v[20:23], off offset:1024
	s_nop 1
	v_cvt_pk_bf16_f32 v20, v40, v41
	v_cvt_pk_bf16_f32 v21, v42, v43
	v_cvt_pk_bf16_f32 v22, v36, v37
	v_cvt_pk_bf16_f32 v23, v38, v39
	global_store_dwordx4 v[62:63], v[20:23], off
	ds_bpermute_b32 v22, v13, v1
	s_waitcnt lgkmcnt(0)
	v_mul_f32_e32 v21, v93, v22
	v_cndmask_b32_e64 v21, v21, -v21, vcc
	v_fmac_f32_e32 v21, v92, v1
	v_cvt_pk_bf16_f32 v1, v21, v3
	global_store_short v[8:9], v1, off
	v_lshl_add_u64 v[8:9], v[8:9], 0, s[18:19]
	s_cbranch_scc1 .LBB0_252
